# v103: v99 with write-through (sc1) stores for the final normalised output (written once, never re-read in the launch)
# baseline (speedup 1.0000x reference)
.Lrf_fin2:
	v_mul_f32_e32 v126, v126, v200
	v_mul_f32_e32 v127, v127, v200
	v_mul_f32_e32 v128, v128, v200
	v_mul_f32_e32 v129, v129, v200
	v_mul_f32_e32 v126, v126, v130
	v_mul_f32_e32 v127, v127, v131
	v_mul_f32_e32 v128, v128, v132
	v_mul_f32_e32 v129, v129, v133
	v_mul_f32_e32 v122, v122, v200
	v_mul_f32_e32 v123, v123, v200
	v_mul_f32_e32 v124, v124, v200
	v_mul_f32_e32 v125, v125, v200
	v_mul_f32_e32 v122, v122, v134
	v_mul_f32_e32 v123, v123, v135
	v_mul_f32_e32 v124, v124, v136
	v_mul_f32_e32 v125, v125, v137
	v_mul_f32_e32 v118, v118, v200
	v_mul_f32_e32 v119, v119, v200
	v_mul_f32_e32 v120, v120, v200
	v_mul_f32_e32 v121, v121, v200
	v_mul_f32_e32 v118, v118, v138
	v_mul_f32_e32 v119, v119, v139
	v_mul_f32_e32 v120, v120, v140
	v_mul_f32_e32 v121, v121, v141
	v_mul_f32_e32 v114, v114, v200
	v_mul_f32_e32 v115, v115, v200
	v_mul_f32_e32 v116, v116, v200
	v_mul_f32_e32 v117, v117, v200
	v_mul_f32_e32 v114, v114, v142
	v_mul_f32_e32 v115, v115, v143
	v_mul_f32_e32 v116, v116, v144
	v_mul_f32_e32 v117, v117, v145
	global_store_dwordx4 v248, v[126:129], s[100:101] offset:0 sc1
	global_store_dwordx4 v248, v[122:125], s[100:101] offset:64 sc1
	global_store_dwordx4 v248, v[118:121], s[100:101] offset:512 sc1
	global_store_dwordx4 v248, v[114:117], s[100:101] offset:576 sc1
	s_add_u32 s8, s100, 0x10000
	s_addc_u32 s9, s101, 0
	v_mul_f32_e32 v110, v110, v204
	v_mul_f32_e32 v111, v111, v204
	v_mul_f32_e32 v112, v112, v204
	v_mul_f32_e32 v113, v113, v204
	v_mul_f32_e32 v110, v110, v130
	v_mul_f32_e32 v111, v111, v131
	v_mul_f32_e32 v112, v112, v132
	v_mul_f32_e32 v113, v113, v133
	v_mul_f32_e32 v106, v106, v204
	v_mul_f32_e32 v107, v107, v204
	v_mul_f32_e32 v108, v108, v204
	v_mul_f32_e32 v109, v109, v204
	v_mul_f32_e32 v106, v106, v134
	v_mul_f32_e32 v107, v107, v135
	v_mul_f32_e32 v108, v108, v136
	v_mul_f32_e32 v109, v109, v137
	v_mul_f32_e32 v102, v102, v204
	v_mul_f32_e32 v103, v103, v204
	v_mul_f32_e32 v104, v104, v204
	v_mul_f32_e32 v105, v105, v204
	v_mul_f32_e32 v102, v102, v138
	v_mul_f32_e32 v103, v103, v139
	v_mul_f32_e32 v104, v104, v140
	v_mul_f32_e32 v105, v105, v141
	v_mul_f32_e32 v98, v98, v204
	v_mul_f32_e32 v99, v99, v204
	v_mul_f32_e32 v100, v100, v204
	v_mul_f32_e32 v101, v101, v204
	v_mul_f32_e32 v98, v98, v142
	v_mul_f32_e32 v99, v99, v143
	v_mul_f32_e32 v100, v100, v144
	v_mul_f32_e32 v101, v101, v145
	global_store_dwordx4 v248, v[110:113], s[8:9] offset:0 sc1
	global_store_dwordx4 v248, v[106:109], s[8:9] offset:64 sc1
	global_store_dwordx4 v248, v[102:105], s[8:9] offset:512 sc1
	global_store_dwordx4 v248, v[98:101], s[8:9] offset:576 sc1
	s_add_u32 s8, s100, 0x20000
	s_addc_u32 s9, s101, 0
	v_mul_f32_e32 v94, v94, v208
	v_mul_f32_e32 v95, v95, v208
	v_mul_f32_e32 v96, v96, v208
	v_mul_f32_e32 v97, v97, v208
	v_mul_f32_e32 v94, v94, v130
	v_mul_f32_e32 v95, v95, v131
	v_mul_f32_e32 v96, v96, v132
	v_mul_f32_e32 v97, v97, v133
	v_mul_f32_e32 v90, v90, v208
	v_mul_f32_e32 v91, v91, v208
	v_mul_f32_e32 v92, v92, v208
	v_mul_f32_e32 v93, v93, v208
	v_mul_f32_e32 v90, v90, v134
	v_mul_f32_e32 v91, v91, v135
	v_mul_f32_e32 v92, v92, v136
	v_mul_f32_e32 v93, v93, v137
	v_mul_f32_e32 v86, v86, v208
	v_mul_f32_e32 v87, v87, v208
	v_mul_f32_e32 v88, v88, v208
	v_mul_f32_e32 v89, v89, v208
	v_mul_f32_e32 v86, v86, v138
	v_mul_f32_e32 v87, v87, v139
	v_mul_f32_e32 v88, v88, v140
	v_mul_f32_e32 v89, v89, v141
	v_mul_f32_e32 v82, v82, v208
	v_mul_f32_e32 v83, v83, v208
	v_mul_f32_e32 v84, v84, v208
	v_mul_f32_e32 v85, v85, v208
	v_mul_f32_e32 v82, v82, v142
	v_mul_f32_e32 v83, v83, v143
	v_mul_f32_e32 v84, v84, v144
	v_mul_f32_e32 v85, v85, v145
	global_store_dwordx4 v248, v[94:97], s[8:9] offset:0 sc1
	global_store_dwordx4 v248, v[90:93], s[8:9] offset:64 sc1
	global_store_dwordx4 v248, v[86:89], s[8:9] offset:512 sc1
	global_store_dwordx4 v248, v[82:85], s[8:9] offset:576 sc1
	s_add_u32 s8, s100, 0x30000
	s_addc_u32 s9, s101, 0
	v_mul_f32_e32 v78, v78, v212
	v_mul_f32_e32 v79, v79, v212
	v_mul_f32_e32 v80, v80, v212
	v_mul_f32_e32 v81, v81, v212
	v_mul_f32_e32 v78, v78, v130
	v_mul_f32_e32 v79, v79, v131
	v_mul_f32_e32 v80, v80, v132
	v_mul_f32_e32 v81, v81, v133
	v_mul_f32_e32 v74, v74, v212
	v_mul_f32_e32 v75, v75, v212
	v_mul_f32_e32 v76, v76, v212
	v_mul_f32_e32 v77, v77, v212
	v_mul_f32_e32 v74, v74, v134
	v_mul_f32_e32 v75, v75, v135
	v_mul_f32_e32 v76, v76, v136
	v_mul_f32_e32 v77, v77, v137
	v_mul_f32_e32 v70, v70, v212
	v_mul_f32_e32 v71, v71, v212
	v_mul_f32_e32 v72, v72, v212
	v_mul_f32_e32 v73, v73, v212
	v_mul_f32_e32 v70, v70, v138
	v_mul_f32_e32 v71, v71, v139
	v_mul_f32_e32 v72, v72, v140
	v_mul_f32_e32 v73, v73, v141
	v_mul_f32_e32 v66, v66, v212
	v_mul_f32_e32 v67, v67, v212
	v_mul_f32_e32 v68, v68, v212
	v_mul_f32_e32 v69, v69, v212
	v_mul_f32_e32 v66, v66, v142
	v_mul_f32_e32 v67, v67, v143
	v_mul_f32_e32 v68, v68, v144
	v_mul_f32_e32 v69, v69, v145
	global_store_dwordx4 v248, v[78:81], s[8:9] offset:0 sc1
	global_store_dwordx4 v248, v[74:77], s[8:9] offset:64 sc1
	global_store_dwordx4 v248, v[70:73], s[8:9] offset:512 sc1
	global_store_dwordx4 v248, v[66:69], s[8:9] offset:576 sc1
	s_add_u32 s8, s100, 0x80000
	s_addc_u32 s9, s101, 0
	v_mul_f32_e32 v62, v62, v216
	v_mul_f32_e32 v63, v63, v216
	v_mul_f32_e32 v64, v64, v216
	v_mul_f32_e32 v65, v65, v216
	v_mul_f32_e32 v62, v62, v130
	v_mul_f32_e32 v63, v63, v131
	v_mul_f32_e32 v64, v64, v132
	v_mul_f32_e32 v65, v65, v133
	v_mul_f32_e32 v58, v58, v216
	v_mul_f32_e32 v59, v59, v216
	v_mul_f32_e32 v60, v60, v216
	v_mul_f32_e32 v61, v61, v216
	v_mul_f32_e32 v58, v58, v134
	v_mul_f32_e32 v59, v59, v135
	v_mul_f32_e32 v60, v60, v136
	v_mul_f32_e32 v61, v61, v137
	v_mul_f32_e32 v54, v54, v216
	v_mul_f32_e32 v55, v55, v216
	v_mul_f32_e32 v56, v56, v216
	v_mul_f32_e32 v57, v57, v216
	v_mul_f32_e32 v54, v54, v138
	v_mul_f32_e32 v55, v55, v139
	v_mul_f32_e32 v56, v56, v140
	v_mul_f32_e32 v57, v57, v141
	v_mul_f32_e32 v50, v50, v216
	v_mul_f32_e32 v51, v51, v216
	v_mul_f32_e32 v52, v52, v216
	v_mul_f32_e32 v53, v53, v216
	v_mul_f32_e32 v50, v50, v142
	v_mul_f32_e32 v51, v51, v143
	v_mul_f32_e32 v52, v52, v144
	v_mul_f32_e32 v53, v53, v145
	global_store_dwordx4 v248, v[62:65], s[8:9] offset:0 sc1
	global_store_dwordx4 v248, v[58:61], s[8:9] offset:64 sc1
	global_store_dwordx4 v248, v[54:57], s[8:9] offset:512 sc1
	global_store_dwordx4 v248, v[50:53], s[8:9] offset:576 sc1
	s_add_u32 s8, s100, 0x90000
	s_addc_u32 s9, s101, 0
	v_mul_f32_e32 v46, v46, v220
	v_mul_f32_e32 v47, v47, v220
	v_mul_f32_e32 v48, v48, v220
	v_mul_f32_e32 v49, v49, v220
	v_mul_f32_e32 v46, v46, v130
	v_mul_f32_e32 v47, v47, v131
	v_mul_f32_e32 v48, v48, v132
	v_mul_f32_e32 v49, v49, v133
	v_mul_f32_e32 v42, v42, v220
	v_mul_f32_e32 v43, v43, v220
	v_mul_f32_e32 v44, v44, v220
	v_mul_f32_e32 v45, v45, v220
	v_mul_f32_e32 v42, v42, v134
	v_mul_f32_e32 v43, v43, v135
	v_mul_f32_e32 v44, v44, v136
	v_mul_f32_e32 v45, v45, v137
	v_mul_f32_e32 v38, v38, v220
	v_mul_f32_e32 v39, v39, v220
	v_mul_f32_e32 v40, v40, v220
	v_mul_f32_e32 v41, v41, v220
	v_mul_f32_e32 v38, v38, v138
	v_mul_f32_e32 v39, v39, v139
	v_mul_f32_e32 v40, v40, v140
	v_mul_f32_e32 v41, v41, v141
	v_mul_f32_e32 v34, v34, v220
	v_mul_f32_e32 v35, v35, v220
	v_mul_f32_e32 v36, v36, v220
	v_mul_f32_e32 v37, v37, v220
	v_mul_f32_e32 v34, v34, v142
	v_mul_f32_e32 v35, v35, v143
	v_mul_f32_e32 v36, v36, v144
	v_mul_f32_e32 v37, v37, v145
	global_store_dwordx4 v248, v[46:49], s[8:9] offset:0 sc1
	global_store_dwordx4 v248, v[42:45], s[8:9] offset:64 sc1
	global_store_dwordx4 v248, v[38:41], s[8:9] offset:512 sc1
	global_store_dwordx4 v248, v[34:37], s[8:9] offset:576 sc1
	s_add_u32 s8, s100, 0xa0000
	s_addc_u32 s9, s101, 0
	v_mul_f32_e32 v30, v30, v240
	v_mul_f32_e32 v31, v31, v240
	v_mul_f32_e32 v32, v32, v240
	v_mul_f32_e32 v33, v33, v240
	v_mul_f32_e32 v30, v30, v130
	v_mul_f32_e32 v31, v31, v131
	v_mul_f32_e32 v32, v32, v132
	v_mul_f32_e32 v33, v33, v133
	v_mul_f32_e32 v26, v26, v240
	v_mul_f32_e32 v27, v27, v240
	v_mul_f32_e32 v28, v28, v240
	v_mul_f32_e32 v29, v29, v240
	v_mul_f32_e32 v26, v26, v134
	v_mul_f32_e32 v27, v27, v135
	v_mul_f32_e32 v28, v28, v136
	v_mul_f32_e32 v29, v29, v137
	v_mul_f32_e32 v22, v22, v240
	v_mul_f32_e32 v23, v23, v240
	v_mul_f32_e32 v24, v24, v240
	v_mul_f32_e32 v25, v25, v240
	v_mul_f32_e32 v22, v22, v138
	v_mul_f32_e32 v23, v23, v139
	v_mul_f32_e32 v24, v24, v140
	v_mul_f32_e32 v25, v25, v141
	v_mul_f32_e32 v18, v18, v240
	v_mul_f32_e32 v19, v19, v240
	v_mul_f32_e32 v20, v20, v240
	v_mul_f32_e32 v21, v21, v240
	v_mul_f32_e32 v18, v18, v142
	v_mul_f32_e32 v19, v19, v143
	v_mul_f32_e32 v20, v20, v144
	v_mul_f32_e32 v21, v21, v145
	global_store_dwordx4 v248, v[30:33], s[8:9] offset:0 sc1
	global_store_dwordx4 v248, v[26:29], s[8:9] offset:64 sc1
	global_store_dwordx4 v248, v[22:25], s[8:9] offset:512 sc1
	global_store_dwordx4 v248, v[18:21], s[8:9] offset:576 sc1
	s_add_u32 s8, s100, 0xb0000
	s_addc_u32 s9, s101, 0
	v_mul_f32_e32 v14, v14, v244
	v_mul_f32_e32 v15, v15, v244
	v_mul_f32_e32 v16, v16, v244
	v_mul_f32_e32 v17, v17, v244
	v_mul_f32_e32 v14, v14, v130
	v_mul_f32_e32 v15, v15, v131
	v_mul_f32_e32 v16, v16, v132
	v_mul_f32_e32 v17, v17, v133
	v_mul_f32_e32 v10, v10, v244
	v_mul_f32_e32 v11, v11, v244
	v_mul_f32_e32 v12, v12, v244
	v_mul_f32_e32 v13, v13, v244
	v_mul_f32_e32 v10, v10, v134
	v_mul_f32_e32 v11, v11, v135
	v_mul_f32_e32 v12, v12, v136
	v_mul_f32_e32 v13, v13, v137
	v_mul_f32_e32 v6, v6, v244
	v_mul_f32_e32 v7, v7, v244
	v_mul_f32_e32 v8, v8, v244
	v_mul_f32_e32 v9, v9, v244
	v_mul_f32_e32 v6, v6, v138
	v_mul_f32_e32 v7, v7, v139
	v_mul_f32_e32 v8, v8, v140
	v_mul_f32_e32 v9, v9, v141
	v_mul_f32_e32 v2, v2, v244
	v_mul_f32_e32 v3, v3, v244
	v_mul_f32_e32 v4, v4, v244
	v_mul_f32_e32 v5, v5, v244
	v_mul_f32_e32 v2, v2, v142
	v_mul_f32_e32 v3, v3, v143
	v_mul_f32_e32 v4, v4, v144
	v_mul_f32_e32 v5, v5, v145
	global_store_dwordx4 v248, v[14:17], s[8:9] offset:0 sc1
	global_store_dwordx4 v248, v[10:13], s[8:9] offset:64 sc1
	global_store_dwordx4 v248, v[6:9], s[8:9] offset:512 sc1
	global_store_dwordx4 v248, v[2:5], s[8:9] offset:576 sc1
	s_branch .LBB0_561
